# k25 + final-phase row loop: counted waits at loop top instead of draining the previous row's stores
# baseline (speedup 1.0000x reference)
; __device__ __forceinline__ void resid_rows(const float* xf_, bf16_t* XB_, const bf16_t* Y_, const float* gain_, float* R_, float* outf_, int rows, int gw, int NGW, int lane) {
;     u32x4 xw[2], yw[2], nxw[2], nyw[2]; f32x4 xv[4], nxv[4];
;     const int last = rows - 1;
;     ...
;     RR_LOAD(xw, yw, xv, gw);
;     for (int row = gw; row < rows; row += NGW) {
.LBB0_1501:
	s_load_dwordx4 s[44:47], s[12:13], 0xc0
	s_load_dwordx2 s[14:15], s[12:13], 0xa8
	s_lshl_b32 s2, s1, 3
	v_mbcnt_lo_u32_b32 v0, -1, v0
	v_mbcnt_hi_u32_b32 v32, -1, v0
	s_waitcnt lgkmcnt(0)
	s_add_u32 s4, s46, 0x19800000
	s_addc_u32 s5, s47, 0
	s_add_u32 s6, s46, 0x2c800000
	s_addc_u32 s7, s47, 0
	s_ashr_i32 s1, s0, 31
	s_lshl_b64 s[12:13], s[0:1], 11
	s_add_u32 s16, s6, s12
	s_addc_u32 s17, s7, s13
	v_ashrrev_i32_e32 v33, 31, v32
	s_add_u32 s12, s4, s12
	v_lshlrev_b64 v[34:35], 4, v[32:33]
	s_addc_u32 s13, s5, s13
	v_lshl_add_u64 v[0:1], s[16:17], 0, v[34:35]
	v_lshl_add_u64 v[4:5], s[12:13], 0, v[34:35]
	global_load_dwordx4 v[8:11], v[0:1], off offset:1024
	global_load_dwordx4 v[12:15], v[0:1], off
	s_nop 0
	global_load_dwordx4 v[0:3], v[4:5], off offset:1024
	s_nop 0
	global_load_dwordx4 v[4:7], v[4:5], off
	s_cmp_lg_u64 s[44:45], 0
	v_lshlrev_b32_e32 v36, 1, v32
	s_cselect_b64 s[12:13], -1, 0
	s_ashr_i32 s1, s3, 31
	s_ashr_i32 s9, s8, 31
	v_ashrrev_i32_e32 v37, 31, v36
	s_add_u32 s8, s3, s8
	v_lshl_add_u64 v[16:17], v[36:37], 4, s[14:15]
	s_mov_b64 s[14:15], 0x3000
	s_addc_u32 s9, s1, s9
	s_ashr_i32 s3, s2, 31
	v_lshl_add_u64 v[38:39], v[16:17], 0, s[14:15]
	s_lshl_b64 s[14:15], s[8:9], 2
	s_lshl_b64 s[16:17], s[2:3], 2
	s_lshl_b64 s[18:19], s[8:9], 11
	s_add_u32 s18, s4, s18
	s_addc_u32 s19, s5, s19
	s_lshl_b64 s[20:21], s[2:3], 11
	s_lshl_b64 s[8:9], s[8:9], 12
	s_add_u32 s1, s36, s8
	s_addc_u32 s8, s37, s9
	s_add_u32 s22, s44, s1
	v_cmp_eq_u32_e64 s[40:41], 0, v32
	s_addc_u32 s23, s45, s8
	s_lshl_b64 s[28:29], s[2:3], 12
	s_waitcnt vmcnt(0)
	s_branch .LBB0_1504

; __device__ __forceinline__ void resid_rows(const float* xf_, bf16_t* XB_, const bf16_t* Y_, const float* gain_, float* R_, float* outf_, int rows, int gw, int NGW, int lane) {
;     ...
;     for (int row = gw; row < rows; row += NGW) {
;         RR_LOAD(nxw, nyw, nxv, row + NGW);
;         float v[16];
;         if (xf_) {
; #pragma unroll
;             for (int j = 0; j < 2; ++j) { const f32x4 a = xv[2 * j], b = xv[2 * j + 1];
;                 v[8 * j + 0] = a.x; v[8 * j + 1] = a.y; v[8 * j + 2] = a.z; v[8 * j + 3] = a.w; v[8 * j + 4] = b.x; v[8 * j + 5] = b.y; v[8 * j + 6] = b.z; v[8 * j + 7] = b.w; } }
;         else {
; #pragma unroll
;             for (int j = 0; j < 2; ++j) { const u32x4 w = xw[j];
;                 v[8 * j + 0] = bf_lo(w.x); v[8 * j + 1] = bf_hi(w.x); v[8 * j + 2] = bf_lo(w.y); v[8 * j + 3] = bf_hi(w.y); v[8 * j + 4] = bf_lo(w.z); v[8 * j + 5] = bf_hi(w.z); v[8 * j + 6] = bf_lo(w.w); v[8 * j + 7] = bf_hi(w.w); } }
;         if (Y_) { float y[16]; float ss = 0.f;
; #pragma unroll
;             for (int j = 0; j < 2; ++j) { const u32x4 w = yw[j];
;                 y[8 * j + 0] = bf_lo(w.x); y[8 * j + 1] = bf_hi(w.x); y[8 * j + 2] = bf_lo(w.y); y[8 * j + 3] = bf_hi(w.y); y[8 * j + 4] = bf_lo(w.z); y[8 * j + 5] = bf_hi(w.z); y[8 * j + 6] = bf_lo(w.w); y[8 * j + 7] = bf_hi(w.w); }
; #pragma unroll
;             for (int i = 0; i < 16; ++i) ss += y[i] * y[i];
;             const float r = 1.0f / sqrtf(wave_sum(ss) * (1.f / DM) + EPS);
;             const GASF f32x4* gp = (const GASF f32x4*)gain_;
; #pragma unroll
;             for (int j = 0; j < 2; ++j) { const f32x4 a = gp[lane * 2 + 128 * j], b = gp[lane * 2 + 1 + 128 * j];
;                 v[8 * j + 0] += y[8 * j + 0] * r * a.x; v[8 * j + 1] += y[8 * j + 1] * r * a.y; v[8 * j + 2] += y[8 * j + 2] * r * a.z; v[8 * j + 3] += y[8 * j + 3] * r * a.w;
;                 v[8 * j + 4] += y[8 * j + 4] * r * b.x; v[8 * j + 5] += y[8 * j + 5] * r * b.y; v[8 * j + 6] += y[8 * j + 6] * r * b.z; v[8 * j + 7] += y[8 * j + 7] * r * b.w; } }
;         if (outf_) { GASF f32x4* p = (GASF f32x4*)(outf_ + (size_t)row * DM);
; #pragma unroll
;             for (int j = 0; j < 2; ++j) { p[lane * 2 + 128 * j] = (f32x4){v[8 * j + 0], v[8 * j + 1], v[8 * j + 2], v[8 * j + 3]}; p[lane * 2 + 1 + 128 * j] = (f32x4){v[8 * j + 4], v[8 * j + 5], v[8 * j + 6], v[8 * j + 7]}; } }
.LBB0_1504:
	s_waitcnt vmcnt(4)
	v_lshlrev_b32_e32 v60, 16, v12
	v_and_b32_e32 v61, 0xffff0000, v12
	v_lshlrev_b32_e32 v56, 16, v14
	v_and_b32_e32 v57, 0xffff0000, v14
	v_lshlrev_b32_e32 v58, 16, v15
	v_and_b32_e32 v59, 0xffff0000, v15
	v_pk_mul_f32 v[14:15], v[60:61], v[60:61]
	v_lshlrev_b32_e32 v62, 16, v13
	v_and_b32_e32 v63, 0xffff0000, v13
	v_pk_mul_f32 v[12:13], v[62:63], v[62:63]
	v_add_f32_e32 v14, v14, v15
	v_add_f32_e32 v12, v12, v14
	s_waitcnt vmcnt(3)
	v_lshlrev_b32_e32 v52, 16, v8
	v_and_b32_e32 v53, 0xffff0000, v8
	v_lshlrev_b32_e32 v54, 16, v9
	v_and_b32_e32 v55, 0xffff0000, v9
	v_pk_mul_f32 v[8:9], v[56:57], v[56:57]
	v_add_f32_e32 v12, v13, v12
	v_add_f32_e32 v8, v8, v12
	v_lshlrev_b32_e32 v48, 16, v10
	v_and_b32_e32 v49, 0xffff0000, v10
	v_lshlrev_b32_e32 v50, 16, v11
	v_and_b32_e32 v51, 0xffff0000, v11
	v_pk_mul_f32 v[10:11], v[58:59], v[58:59]
	v_add_f32_e32 v8, v9, v8
	s_waitcnt vmcnt(3)
	v_mov_b64_e32 v[18:19], v[6:7]
	v_add_f32_e32 v8, v10, v8
	v_mov_b64_e32 v[16:17], v[4:5]
	v_pk_mul_f32 v[4:5], v[52:53], v[52:53]
	v_add_f32_e32 v8, v11, v8
	v_add_f32_e32 v4, v4, v8
	v_pk_mul_f32 v[6:7], v[54:55], v[54:55]
	v_add_f32_e32 v4, v5, v4
	v_mov_b64_e32 v[22:23], v[2:3]
	v_add_f32_e32 v4, v6, v4
	v_mov_b64_e32 v[20:21], v[0:1]
	v_pk_mul_f32 v[0:1], v[48:49], v[48:49]
	v_add_f32_e32 v4, v7, v4
	v_add_f32_e32 v0, v0, v4
	s_add_i32 s0, s0, s2
	v_pk_mul_f32 v[2:3], v[50:51], v[50:51]
	v_add_f32_e32 v0, v1, v0
	s_min_i32 s8, s0, 0x7fff
	v_add_f32_e32 v0, v2, v0
	s_ashr_i32 s9, s8, 31
	v_add_f32_e32 v8, v3, v0
	s_lshl_b64 s[30:31], s[8:9], 11
	ds_swizzle_b32 v9, v8 offset:swizzle(SWAP,1)
	s_add_u32 s34, s4, s30
	s_addc_u32 s35, s5, s31
	s_add_u32 s8, s6, s30
	global_load_dwordx4 v[24:27], v[38:39], off offset:16
	global_load_dwordx4 v[28:31], v[38:39], off
	global_load_dwordx4 v[40:43], v[38:39], off offset:2064
	global_load_dwordx4 v[44:47], v[38:39], off offset:2048
	s_addc_u32 s9, s7, s31
	v_lshl_add_u64 v[0:1], s[34:35], 0, v[34:35]
	s_waitcnt lgkmcnt(0)
	v_add_f32_e32 v64, v8, v9
	v_lshl_add_u64 v[8:9], s[8:9], 0, v[34:35]
	global_load_dwordx4 v[4:7], v[0:1], off
	s_nop 0
	global_load_dwordx4 v[0:3], v[0:1], off offset:1024
	s_nop 0
	global_load_dwordx4 v[12:15], v[8:9], off
	s_nop 0
	global_load_dwordx4 v[8:11], v[8:9], off offset:1024
	ds_swizzle_b32 v65, v64 offset:swizzle(SWAP,2)
	v_lshlrev_b32_e32 v68, 16, v20
	v_and_b32_e32 v69, 0xffff0000, v20
	v_and_b32_e32 v71, 0xffff0000, v21
	v_lshlrev_b32_e32 v20, 16, v18
	s_waitcnt lgkmcnt(0)
	v_add_f32_e32 v66, v64, v65
	ds_swizzle_b32 v67, v66 offset:swizzle(SWAP,4)
	v_lshlrev_b32_e32 v64, 16, v22
	v_and_b32_e32 v65, 0xffff0000, v22
	s_waitcnt lgkmcnt(0)
	v_add_f32_e32 v22, v66, v67
	ds_swizzle_b32 v70, v22 offset:swizzle(SWAP,8)
	v_lshlrev_b32_e32 v66, 16, v23
	v_and_b32_e32 v67, 0xffff0000, v23
	s_waitcnt lgkmcnt(0)
	v_add_f32_e32 v22, v22, v70
	ds_swizzle_b32 v23, v22 offset:swizzle(SWAP,16)
	v_lshlrev_b32_e32 v70, 16, v21
	v_and_b32_e32 v21, 0xffff0000, v18
	s_waitcnt lgkmcnt(0)
	v_add_f32_e32 v18, v22, v23
	v_mov_b32_e32 v22, v18
	s_nop 1
	v_permlane32_swap_b32_e32 v18, v22
	v_add_f32_e32 v18, v18, v22
	v_fmamk_f32 v18, v18, 0x3a800000, v204
	v_mul_f32_e32 v22, 0x4f800000, v18
	v_cmp_gt_f32_e32 vcc, s81, v18
	v_and_b32_e32 v23, 0xffff0000, v19
	s_nop 0
	v_cndmask_b32_e32 v72, v18, v22, vcc
	v_sqrt_f32_e32 v73, v72
	v_lshlrev_b32_e32 v22, 16, v19
	v_lshlrev_b32_e32 v18, 16, v16
	v_add_u32_e32 v19, -1, v73
	v_fma_f32 v74, -v19, v73, v72
	v_cmp_ge_f32_e64 s[42:43], 0, v74
	v_add_u32_e32 v74, 1, v73
	s_nop 0
	v_cndmask_b32_e64 v19, v73, v19, s[42:43]
	v_fma_f32 v73, -v74, v73, v72
	v_cmp_lt_f32_e64 s[42:43], 0, v73
	s_nop 1
	v_cndmask_b32_e64 v19, v19, v74, s[42:43]
	v_mul_f32_e32 v73, 0x37800000, v19
	v_cndmask_b32_e32 v19, v19, v73, vcc
	v_cmp_class_f32_e32 vcc, v72, v205
	v_and_b32_e32 v73, 0xffff0000, v17
	s_nop 0
	v_cndmask_b32_e32 v74, v19, v72, vcc
	v_div_scale_f32 v75, s[8:9], v74, v74, 1.0
	v_rcp_f32_e32 v76, v75
	v_and_b32_e32 v19, 0xffff0000, v16
	v_lshlrev_b32_e32 v72, 16, v17
	v_fma_f32 v16, -v75, v76, 1.0
	v_fmac_f32_e32 v76, v16, v76
	v_div_scale_f32 v16, vcc, 1.0, v74, 1.0
	v_mul_f32_e32 v17, v16, v76
	v_fma_f32 v77, -v75, v17, v16
	v_fmac_f32_e32 v17, v77, v76
	v_fma_f32 v16, -v75, v17, v16
	v_div_fmas_f32 v16, v16, v76, v17
	v_div_fixup_f32 v74, v16, v74, 1.0
	v_pk_mul_f32 v[16:17], v[74:75], v[60:61] op_sel_hi:[0,1]
	s_waitcnt vmcnt(6)
	v_pk_fma_f32 v[16:17], v[28:29], v[16:17], v[18:19]
	v_pk_mul_f32 v[28:29], v[74:75], v[56:57] op_sel_hi:[0,1]
	v_pk_mul_f32 v[18:19], v[74:75], v[62:63] op_sel_hi:[0,1]
	v_pk_fma_f32 v[20:21], v[24:25], v[28:29], v[20:21]
	v_pk_mul_f32 v[24:25], v[74:75], v[58:59] op_sel_hi:[0,1]
	v_pk_fma_f32 v[18:19], v[30:31], v[18:19], v[72:73]
	v_pk_fma_f32 v[22:23], v[26:27], v[24:25], v[22:23]
	v_pk_mul_f32 v[24:25], v[74:75], v[52:53] op_sel_hi:[0,1]
	v_pk_mul_f32 v[26:27], v[74:75], v[54:55] op_sel_hi:[0,1]
	v_pk_mul_f32 v[28:29], v[74:75], v[48:49] op_sel_hi:[0,1]
	v_pk_mul_f32 v[30:31], v[74:75], v[50:51] op_sel_hi:[0,1]
	s_waitcnt vmcnt(4)
	v_pk_fma_f32 v[24:25], v[44:45], v[24:25], v[68:69]
	v_pk_fma_f32 v[26:27], v[46:47], v[26:27], v[70:71]
	v_pk_fma_f32 v[28:29], v[40:41], v[28:29], v[64:65]
	s_andn2_b64 vcc, exec, s[12:13]
	v_pk_fma_f32 v[30:31], v[42:43], v[30:31], v[66:67]
	s_cbranch_vccnz .LBB0_1506
	v_lshl_add_u64 v[40:41], v[36:37], 4, s[22:23]
	global_store_dwordx4 v[40:41], v[16:19], off
	global_store_dwordx4 v[40:41], v[20:23], off offset:16
	global_store_dwordx4 v[40:41], v[24:27], off offset:2048
	global_store_dwordx4 v[40:41], v[28:31], off offset:2064
	s_cbranch_execnz .LBB0_1503
	s_branch .LBB0_1507
